# barrier leaders touch the first two K-tiles of the next GEMM phase's first weight tile before polling (weights in L2 when the prologue loads them)
# speedup vs baseline: 1.0013x; 1.0008x over previous
; __device__ __forceinline__ void xcd_local_bar(unsigned* ctr, unsigned target, bool leader) {
;     asm volatile("s_waitcnt vmcnt(0) lgkmcnt(0)" ::: "memory");
;     __syncthreads();
;     if (leader) {
;         __hip_atomic_fetch_add(ctr, 1u, __ATOMIC_RELAXED, __HIP_MEMORY_SCOPE_AGENT);
;         while (__hip_atomic_load(ctr, __ATOMIC_RELAXED, __HIP_MEMORY_SCOPE_AGENT) < target) __builtin_amdgcn_s_sleep(1);
;         __builtin_amdgcn_fence(__ATOMIC_ACQUIRE, "agent");
;         asm volatile("s_waitcnt vmcnt(0)" ::: "memory");
;     }
;     __syncthreads();
; }
.LBB0_481:
	s_waitcnt vmcnt(0) lgkmcnt(0)
	s_add_i32 s24, s59, s54
	s_barrier
	s_and_b64 vcc, exec, s[4:5]
	s_cbranch_vccnz .Ltb0_skip
	s_lshr_b32 s100, s2, 6
	s_mul_i32 s100, s100, 0x80000
	s_add_u32 s98, s18, 0x900000
	s_addc_u32 s99, s19, 0
	s_add_u32 s98, s98, s100
	s_addc_u32 s99, s99, 0
	v_mul_u32_u24_e32 v254, 0x800, v212
	global_load_dword v255, v254, s[98:99]
	global_load_dword v255, v254, s[98:99] offset:128
	s_add_u32 s98, s98, 0x20000
	s_addc_u32 s99, s99, 0
	global_load_dword v255, v254, s[98:99]
	global_load_dword v255, v254, s[98:99] offset:128
	s_add_u32 s98, s98, 0x20000
	s_addc_u32 s99, s99, 0
	global_load_dword v255, v254, s[98:99]
	global_load_dword v255, v254, s[98:99] offset:128
	s_add_u32 s98, s98, 0x20000
	s_addc_u32 s99, s99, 0
	global_load_dword v255, v254, s[98:99]
	global_load_dword v255, v254, s[98:99] offset:128
.Ltb0_skip:
	s_and_saveexec_b64 s[8:9], s[14:15]
	s_cbranch_execz .LBB0_487
	s_mov_b64 s[14:15], exec
	v_readlane_b32 s25, v248, 4
	s_lshl_b32 s25, s25, 2
	v_mbcnt_lo_u32_b32 v0, s14, 0
	s_add_u32 s10, s10, s25
	v_mbcnt_hi_u32_b32 v0, s15, v0
	s_addc_u32 s11, s11, 0
	v_cmp_eq_u32_e32 vcc, 0, v0
	s_and_saveexec_b64 s[26:27], vcc
	s_cbranch_execz .LBB0_484
	s_bcnt1_i32_b64 s14, s[14:15]
	v_mov_b32_e32 v0, 0
	v_mov_b32_e32 v1, s14
	global_atomic_add v0, v1, s[10:11] offset:256

; __device__ __forceinline__ void xcd_local_bar(unsigned* ctr, unsigned target, bool leader) {
;     asm volatile("s_waitcnt vmcnt(0) lgkmcnt(0)" ::: "memory");
;     __syncthreads();
;     if (leader) {
;         __hip_atomic_fetch_add(ctr, 1u, __ATOMIC_RELAXED, __HIP_MEMORY_SCOPE_AGENT);
;         while (__hip_atomic_load(ctr, __ATOMIC_RELAXED, __HIP_MEMORY_SCOPE_AGENT) < target) __builtin_amdgcn_s_sleep(1);
;         __builtin_amdgcn_fence(__ATOMIC_ACQUIRE, "agent");
;         asm volatile("s_waitcnt vmcnt(0)" ::: "memory");
;     }
;     __syncthreads();
; }
.LBB0_524:
	s_waitcnt vmcnt(0) lgkmcnt(0)
	s_add_i32 s24, s59, s54
	s_barrier
	s_and_b64 vcc, exec, s[4:5]
	s_cbranch_vccnz .Ltb1_skip
	s_lshr_b32 s100, s2, 6
	s_mul_i32 s100, s100, 0x80000
	s_add_u32 s98, s18, 0xb00000
	s_addc_u32 s99, s19, 0
	s_add_u32 s98, s98, s100
	s_addc_u32 s99, s99, 0
	v_mul_u32_u24_e32 v254, 0x800, v212
	global_load_dword v255, v254, s[98:99]
	global_load_dword v255, v254, s[98:99] offset:128
	s_add_u32 s98, s98, 0x20000
	s_addc_u32 s99, s99, 0
	global_load_dword v255, v254, s[98:99]
	global_load_dword v255, v254, s[98:99] offset:128
	s_add_u32 s98, s98, 0x20000
	s_addc_u32 s99, s99, 0
	global_load_dword v255, v254, s[98:99]
	global_load_dword v255, v254, s[98:99] offset:128
	s_add_u32 s98, s98, 0x20000
	s_addc_u32 s99, s99, 0
	global_load_dword v255, v254, s[98:99]
	global_load_dword v255, v254, s[98:99] offset:128
.Ltb1_skip:
	s_and_saveexec_b64 s[10:11], s[26:27]
	s_cbranch_execz .LBB0_530
	s_mov_b64 s[26:27], exec
	v_readlane_b32 s25, v248, 4
	s_lshl_b32 s25, s25, 2
	v_mbcnt_lo_u32_b32 v0, s26, 0
	s_add_u32 s12, s12, s25
	v_mbcnt_hi_u32_b32 v0, s27, v0
	s_addc_u32 s13, s13, 0
	v_cmp_eq_u32_e32 vcc, 0, v0
	s_and_saveexec_b64 s[28:29], vcc
	s_cbranch_execz .LBB0_527
	s_bcnt1_i32_b64 s25, s[26:27]
	v_mov_b32_e32 v0, 0
	v_mov_b32_e32 v1, s25
	global_atomic_add v0, v1, s[12:13] offset:256

; __device__ __forceinline__ void xcd_local_bar(unsigned* ctr, unsigned target, bool leader) {
;     asm volatile("s_waitcnt vmcnt(0) lgkmcnt(0)" ::: "memory");
;     __syncthreads();
;     if (leader) {
;         __hip_atomic_fetch_add(ctr, 1u, __ATOMIC_RELAXED, __HIP_MEMORY_SCOPE_AGENT);
;         while (__hip_atomic_load(ctr, __ATOMIC_RELAXED, __HIP_MEMORY_SCOPE_AGENT) < target) __builtin_amdgcn_s_sleep(1);
;         __builtin_amdgcn_fence(__ATOMIC_ACQUIRE, "agent");
;         asm volatile("s_waitcnt vmcnt(0)" ::: "memory");
;     }
;     __syncthreads();
; }
.LBB0_583:
	s_waitcnt vmcnt(0) lgkmcnt(0)
	s_add_i32 s24, s59, s54
	s_waitcnt lgkmcnt(0)
	s_barrier
	s_and_b64 vcc, exec, s[4:5]
	s_cbranch_vccnz .Ltb2_skip
	s_lshr_b32 s100, s2, 6
	s_and_b32 s100, s100, 1
	s_mul_i32 s100, s100, 0x80000
	s_add_u32 s98, s18, 0xd00000
	s_addc_u32 s99, s19, 0
	s_add_u32 s98, s98, s100
	s_addc_u32 s99, s99, 0
	v_mul_u32_u24_e32 v254, 0x800, v212
	global_load_dword v255, v254, s[98:99]
	global_load_dword v255, v254, s[98:99] offset:128
	s_add_u32 s98, s98, 0x20000
	s_addc_u32 s99, s99, 0
	global_load_dword v255, v254, s[98:99]
	global_load_dword v255, v254, s[98:99] offset:128
	s_add_u32 s98, s98, 0x20000
	s_addc_u32 s99, s99, 0
	global_load_dword v255, v254, s[98:99]
	global_load_dword v255, v254, s[98:99] offset:128
	s_add_u32 s98, s98, 0x20000
	s_addc_u32 s99, s99, 0
	global_load_dword v255, v254, s[98:99]
	global_load_dword v255, v254, s[98:99] offset:128
.Ltb2_skip:
	s_and_saveexec_b64 s[12:13], s[26:27]
	s_cbranch_execz .LBB0_589
	s_mov_b64 s[26:27], exec
	v_readlane_b32 s25, v248, 4
	s_lshl_b32 s25, s25, 2
	v_mbcnt_lo_u32_b32 v0, s26, 0
	s_add_u32 s14, s14, s25
	v_mbcnt_hi_u32_b32 v0, s27, v0
	s_addc_u32 s15, s15, 0
	v_cmp_eq_u32_e32 vcc, 0, v0
	s_and_saveexec_b64 s[28:29], vcc
	s_cbranch_execz .LBB0_586
	s_bcnt1_i32_b64 s25, s[26:27]
	v_mov_b32_e32 v0, 0
	v_mov_b32_e32 v1, s25
	global_atomic_add v0, v1, s[14:15] offset:256

; __device__ __forceinline__ void xcd_local_bar(unsigned* ctr, unsigned target, bool leader) {
;     asm volatile("s_waitcnt vmcnt(0) lgkmcnt(0)" ::: "memory");
;     __syncthreads();
;     if (leader) {
;         __hip_atomic_fetch_add(ctr, 1u, __ATOMIC_RELAXED, __HIP_MEMORY_SCOPE_AGENT);
;         while (__hip_atomic_load(ctr, __ATOMIC_RELAXED, __HIP_MEMORY_SCOPE_AGENT) < target) __builtin_amdgcn_s_sleep(1);
;         __builtin_amdgcn_fence(__ATOMIC_ACQUIRE, "agent");
;         asm volatile("s_waitcnt vmcnt(0)" ::: "memory");
;     }
;     __syncthreads();
; }
.LBB0_664:
	s_waitcnt vmcnt(0) lgkmcnt(0)
	s_add_i32 s24, s59, s54
	s_barrier
	s_and_b64 vcc, exec, s[4:5]
	s_cbranch_vccnz .Ltb4_skip
	s_lshr_b32 s100, s2, 6
	s_mul_i32 s100, s100, 0x40000
	s_add_u32 s98, s18, 0x1000000
	s_addc_u32 s99, s19, 0
	s_add_u32 s98, s98, s100
	s_addc_u32 s99, s99, 0
	v_mul_u32_u24_e32 v254, 0x400, v212
	global_load_dword v255, v254, s[98:99]
	global_load_dword v255, v254, s[98:99] offset:128
	s_add_u32 s98, s98, 0x10000
	s_addc_u32 s99, s99, 0
	global_load_dword v255, v254, s[98:99]
	global_load_dword v255, v254, s[98:99] offset:128
	s_add_u32 s98, s98, 0x10000
	s_addc_u32 s99, s99, 0
	global_load_dword v255, v254, s[98:99]
	global_load_dword v255, v254, s[98:99] offset:128
	s_add_u32 s98, s98, 0x10000
	s_addc_u32 s99, s99, 0
	global_load_dword v255, v254, s[98:99]
	global_load_dword v255, v254, s[98:99] offset:128

; __device__ __forceinline__ void xcd_local_bar(unsigned* ctr, unsigned target, bool leader) {
;     asm volatile("s_waitcnt vmcnt(0) lgkmcnt(0)" ::: "memory");
;     __syncthreads();
;     if (leader) {
;         __hip_atomic_fetch_add(ctr, 1u, __ATOMIC_RELAXED, __HIP_MEMORY_SCOPE_AGENT);
;         while (__hip_atomic_load(ctr, __ATOMIC_RELAXED, __HIP_MEMORY_SCOPE_AGENT) < target) __builtin_amdgcn_s_sleep(1);
;         __builtin_amdgcn_fence(__ATOMIC_ACQUIRE, "agent");
;         asm volatile("s_waitcnt vmcnt(0)" ::: "memory");
;     }
;     __syncthreads();
; }
.LBB0_687:
	s_waitcnt vmcnt(0) lgkmcnt(0)
	s_add_i32 s24, s59, s54
	s_waitcnt lgkmcnt(0)
	s_barrier
	s_and_b64 vcc, exec, s[4:5]
	s_cbranch_vccnz .Ltb5_skip
	s_lshr_b32 s100, s2, 6
	s_mul_i32 s100, s100, 0x80000
	s_add_u32 s98, s18, 0x1100000
	s_addc_u32 s99, s19, 0
	s_add_u32 s98, s98, s100
	s_addc_u32 s99, s99, 0
	v_mul_u32_u24_e32 v254, 0x800, v212
	global_load_dword v255, v254, s[98:99]
	global_load_dword v255, v254, s[98:99] offset:128
	s_add_u32 s98, s98, 0x20000
	s_addc_u32 s99, s99, 0
	global_load_dword v255, v254, s[98:99]
	global_load_dword v255, v254, s[98:99] offset:128
	s_add_u32 s98, s98, 0x20000
	s_addc_u32 s99, s99, 0
	global_load_dword v255, v254, s[98:99]
	global_load_dword v255, v254, s[98:99] offset:128
	s_add_u32 s98, s98, 0x20000
	s_addc_u32 s99, s99, 0
	global_load_dword v255, v254, s[98:99]
	global_load_dword v255, v254, s[98:99] offset:128

; __device__ __forceinline__ void xcd_local_bar(unsigned* ctr, unsigned target, bool leader) {
;     asm volatile("s_waitcnt vmcnt(0) lgkmcnt(0)" ::: "memory");
;     __syncthreads();
;     if (leader) {
;         __hip_atomic_fetch_add(ctr, 1u, __ATOMIC_RELAXED, __HIP_MEMORY_SCOPE_AGENT);
;         while (__hip_atomic_load(ctr, __ATOMIC_RELAXED, __HIP_MEMORY_SCOPE_AGENT) < target) __builtin_amdgcn_s_sleep(1);
;         __builtin_amdgcn_fence(__ATOMIC_ACQUIRE, "agent");
;         asm volatile("s_waitcnt vmcnt(0)" ::: "memory");
;     }
;     __syncthreads();
; }
.LBB0_760:
	s_waitcnt vmcnt(0) lgkmcnt(0)
	s_add_i32 s24, s59, s54
	s_barrier
	s_and_b64 vcc, exec, s[4:5]
	s_cbranch_vccnz .Ltb6_skip
	s_lshr_b32 s100, s2, 6
	s_mul_i32 s100, s100, 0x160000
	s_add_u32 s98, s18, 0x1c00000
	s_addc_u32 s99, s19, 0
	s_add_u32 s98, s98, s100
	s_addc_u32 s99, s99, 0
	v_mul_u32_u24_e32 v254, 0x1600, v212
	global_load_dword v255, v254, s[98:99]
	global_load_dword v255, v254, s[98:99] offset:128
	s_add_u32 s98, s98, 0x58000
	s_addc_u32 s99, s99, 0
	global_load_dword v255, v254, s[98:99]
	global_load_dword v255, v254, s[98:99] offset:128
	s_add_u32 s98, s98, 0x58000
	s_addc_u32 s99, s99, 0
	global_load_dword v255, v254, s[98:99]
	global_load_dword v255, v254, s[98:99] offset:128
	s_add_u32 s98, s98, 0x58000
	s_addc_u32 s99, s99, 0
	global_load_dword v255, v254, s[98:99]
	global_load_dword v255, v254, s[98:99] offset:128
